# scan15 loads issued up front (no per-step vmcnt(0)); attention epilogue staged through LDS into dwordx4 stores
# baseline (speedup 1.0000x reference)
; #define LAS __attribute__((address_space(3)))
; __device__ __forceinline__ void phase_scan15(const Args& a, LAS unsigned char* lds, int wv_) { LAUNDER_IDS;
;     ...
;     unsigned char* ws = a.ws; const int tid = tidx_, seg = tid >> 6, cpl = tid & 63, idx = bidx_ * 64 + cpl, dir = idx >> 10, ch = (idx & 1023) * 2;
;     const float* GA = (const float*)(ws + WS_AGGA) + (size_t)dir * 256 * DM + ch; const float* GB = (const float*)(ws + WS_AGGB) + (size_t)dir * 256 * DM + ch; float* CR = (float*)(ws + WS_CARRY) + (size_t)dir * 256 * DM + ch;
;     LAS f32x4* seg_agg = (LAS f32x4*)lds;
;     f32x2 A = {1.f, 1.f}, B = {0.f, 0.f};
; #pragma unroll 8
;     for (int i = 0; i < 32; ++i) { const int c = dir ? 255 - (seg * 32 + i) : seg * 32 + i; const f32x2 av = *(const f32x2*)(GA + (size_t)c * DM), bv = *(const f32x2*)(GB + (size_t)c * DM); B = av * B + bv; A = A * av; }
.LBB0_156:
	s_and_b32 s100, vcc_lo, 0x4000
	s_sub_i32 s100, s100, 0x2000
	s_ashr_i32 s101, s100, 31
	v_add_u32_e32 v10, 7, v12
	v_cndmask_b32_e32 v10, v10, v9, vcc
	v_lshlrev_b32_e32 v148, 13, v10
	v_mov_b32_e32 v149, 0
	v_lshl_add_u64 v[4:5], v[4:5], 0, v[148:149]
	v_lshl_add_u64 v[6:7], v[6:7], 0, v[148:149]
	global_load_dwordx2 v[20:21], v[4:5], off
	global_load_dwordx2 v[84:85], v[6:7], off
	v_lshl_add_u64 v[4:5], v[4:5], 0, s[100:101]
	v_lshl_add_u64 v[6:7], v[6:7], 0, s[100:101]
	global_load_dwordx2 v[22:23], v[4:5], off
	global_load_dwordx2 v[86:87], v[6:7], off
	v_lshl_add_u64 v[4:5], v[4:5], 0, s[100:101]
	v_lshl_add_u64 v[6:7], v[6:7], 0, s[100:101]
	global_load_dwordx2 v[24:25], v[4:5], off
	global_load_dwordx2 v[88:89], v[6:7], off
	v_lshl_add_u64 v[4:5], v[4:5], 0, s[100:101]
	v_lshl_add_u64 v[6:7], v[6:7], 0, s[100:101]
	global_load_dwordx2 v[26:27], v[4:5], off
	global_load_dwordx2 v[90:91], v[6:7], off
	v_lshl_add_u64 v[4:5], v[4:5], 0, s[100:101]
	v_lshl_add_u64 v[6:7], v[6:7], 0, s[100:101]
	global_load_dwordx2 v[28:29], v[4:5], off
	global_load_dwordx2 v[92:93], v[6:7], off
	v_lshl_add_u64 v[4:5], v[4:5], 0, s[100:101]
	v_lshl_add_u64 v[6:7], v[6:7], 0, s[100:101]
	global_load_dwordx2 v[30:31], v[4:5], off
	global_load_dwordx2 v[94:95], v[6:7], off
	v_lshl_add_u64 v[4:5], v[4:5], 0, s[100:101]
	v_lshl_add_u64 v[6:7], v[6:7], 0, s[100:101]
	global_load_dwordx2 v[32:33], v[4:5], off
	global_load_dwordx2 v[96:97], v[6:7], off
	v_lshl_add_u64 v[4:5], v[4:5], 0, s[100:101]
	v_lshl_add_u64 v[6:7], v[6:7], 0, s[100:101]
	global_load_dwordx2 v[34:35], v[4:5], off
	global_load_dwordx2 v[98:99], v[6:7], off
	v_lshl_add_u64 v[4:5], v[4:5], 0, s[100:101]
	v_lshl_add_u64 v[6:7], v[6:7], 0, s[100:101]
	global_load_dwordx2 v[36:37], v[4:5], off
	global_load_dwordx2 v[100:101], v[6:7], off
	v_lshl_add_u64 v[4:5], v[4:5], 0, s[100:101]
	v_lshl_add_u64 v[6:7], v[6:7], 0, s[100:101]
	global_load_dwordx2 v[38:39], v[4:5], off
	global_load_dwordx2 v[102:103], v[6:7], off
	v_lshl_add_u64 v[4:5], v[4:5], 0, s[100:101]
	v_lshl_add_u64 v[6:7], v[6:7], 0, s[100:101]
	global_load_dwordx2 v[40:41], v[4:5], off
	global_load_dwordx2 v[104:105], v[6:7], off
	v_lshl_add_u64 v[4:5], v[4:5], 0, s[100:101]
	v_lshl_add_u64 v[6:7], v[6:7], 0, s[100:101]
	global_load_dwordx2 v[42:43], v[4:5], off
	global_load_dwordx2 v[106:107], v[6:7], off
	v_lshl_add_u64 v[4:5], v[4:5], 0, s[100:101]
	v_lshl_add_u64 v[6:7], v[6:7], 0, s[100:101]
	global_load_dwordx2 v[44:45], v[4:5], off
	global_load_dwordx2 v[108:109], v[6:7], off
	v_lshl_add_u64 v[4:5], v[4:5], 0, s[100:101]
	v_lshl_add_u64 v[6:7], v[6:7], 0, s[100:101]
	global_load_dwordx2 v[46:47], v[4:5], off
	global_load_dwordx2 v[110:111], v[6:7], off
	v_lshl_add_u64 v[4:5], v[4:5], 0, s[100:101]
	v_lshl_add_u64 v[6:7], v[6:7], 0, s[100:101]
	global_load_dwordx2 v[48:49], v[4:5], off
	global_load_dwordx2 v[112:113], v[6:7], off
	v_lshl_add_u64 v[4:5], v[4:5], 0, s[100:101]
	v_lshl_add_u64 v[6:7], v[6:7], 0, s[100:101]
	global_load_dwordx2 v[50:51], v[4:5], off
	global_load_dwordx2 v[114:115], v[6:7], off
	v_lshl_add_u64 v[4:5], v[4:5], 0, s[100:101]
	v_lshl_add_u64 v[6:7], v[6:7], 0, s[100:101]
	global_load_dwordx2 v[52:53], v[4:5], off
	global_load_dwordx2 v[116:117], v[6:7], off
	v_lshl_add_u64 v[4:5], v[4:5], 0, s[100:101]
	v_lshl_add_u64 v[6:7], v[6:7], 0, s[100:101]
	global_load_dwordx2 v[54:55], v[4:5], off
	global_load_dwordx2 v[118:119], v[6:7], off
	v_lshl_add_u64 v[4:5], v[4:5], 0, s[100:101]
	v_lshl_add_u64 v[6:7], v[6:7], 0, s[100:101]
	global_load_dwordx2 v[56:57], v[4:5], off
	global_load_dwordx2 v[120:121], v[6:7], off
	v_lshl_add_u64 v[4:5], v[4:5], 0, s[100:101]
	v_lshl_add_u64 v[6:7], v[6:7], 0, s[100:101]
	global_load_dwordx2 v[58:59], v[4:5], off
	global_load_dwordx2 v[122:123], v[6:7], off
	v_lshl_add_u64 v[4:5], v[4:5], 0, s[100:101]
	v_lshl_add_u64 v[6:7], v[6:7], 0, s[100:101]
	global_load_dwordx2 v[60:61], v[4:5], off
	global_load_dwordx2 v[124:125], v[6:7], off
	v_lshl_add_u64 v[4:5], v[4:5], 0, s[100:101]
	v_lshl_add_u64 v[6:7], v[6:7], 0, s[100:101]
	global_load_dwordx2 v[62:63], v[4:5], off
	global_load_dwordx2 v[126:127], v[6:7], off
	v_lshl_add_u64 v[4:5], v[4:5], 0, s[100:101]
	v_lshl_add_u64 v[6:7], v[6:7], 0, s[100:101]
	global_load_dwordx2 v[64:65], v[4:5], off
	global_load_dwordx2 v[128:129], v[6:7], off
	v_lshl_add_u64 v[4:5], v[4:5], 0, s[100:101]
	v_lshl_add_u64 v[6:7], v[6:7], 0, s[100:101]
	global_load_dwordx2 v[66:67], v[4:5], off
	global_load_dwordx2 v[130:131], v[6:7], off
	v_lshl_add_u64 v[4:5], v[4:5], 0, s[100:101]
	v_lshl_add_u64 v[6:7], v[6:7], 0, s[100:101]
	global_load_dwordx2 v[68:69], v[4:5], off
	global_load_dwordx2 v[132:133], v[6:7], off
	v_lshl_add_u64 v[4:5], v[4:5], 0, s[100:101]
	v_lshl_add_u64 v[6:7], v[6:7], 0, s[100:101]
	global_load_dwordx2 v[70:71], v[4:5], off
	global_load_dwordx2 v[134:135], v[6:7], off
	v_lshl_add_u64 v[4:5], v[4:5], 0, s[100:101]
	v_lshl_add_u64 v[6:7], v[6:7], 0, s[100:101]
	global_load_dwordx2 v[72:73], v[4:5], off
	global_load_dwordx2 v[136:137], v[6:7], off
	v_lshl_add_u64 v[4:5], v[4:5], 0, s[100:101]
	v_lshl_add_u64 v[6:7], v[6:7], 0, s[100:101]
	global_load_dwordx2 v[74:75], v[4:5], off
	global_load_dwordx2 v[138:139], v[6:7], off
	v_lshl_add_u64 v[4:5], v[4:5], 0, s[100:101]
	v_lshl_add_u64 v[6:7], v[6:7], 0, s[100:101]
	global_load_dwordx2 v[76:77], v[4:5], off
	global_load_dwordx2 v[140:141], v[6:7], off
	v_lshl_add_u64 v[4:5], v[4:5], 0, s[100:101]
	v_lshl_add_u64 v[6:7], v[6:7], 0, s[100:101]
	global_load_dwordx2 v[78:79], v[4:5], off
	global_load_dwordx2 v[142:143], v[6:7], off
	v_lshl_add_u64 v[4:5], v[4:5], 0, s[100:101]
	v_lshl_add_u64 v[6:7], v[6:7], 0, s[100:101]
	global_load_dwordx2 v[80:81], v[4:5], off
	global_load_dwordx2 v[144:145], v[6:7], off
	v_lshl_add_u64 v[4:5], v[4:5], 0, s[100:101]
	v_lshl_add_u64 v[6:7], v[6:7], 0, s[100:101]
	global_load_dwordx2 v[82:83], v[4:5], off
	global_load_dwordx2 v[146:147], v[6:7], off
	s_waitcnt vmcnt(48)
; __device__ __forceinline__ void phase_scan15(const Args& a, LAS unsigned char* lds, int wv_) { LAUNDER_IDS;
;     ...
;     for (int i = 0; i < 32; ++i) { const int c = dir ? 255 - (seg * 32 + i) : seg * 32 + i; const f32x2 av = *(const f32x2*)(GA + (size_t)c * DM), bv = *(const f32x2*)(GB + (size_t)c * DM); B = av * B + bv; A = A * av; }
;     seg_agg[seg * 64 + cpl] = (f32x4){A.x, A.y, B.x, B.y};
;     __syncthreads();
;     f32x2 carry = {0.f, 0.f};
;     for (int k = 0; k < seg; ++k) { const f32x4 g = seg_agg[k * 64 + cpl]; carry = (f32x2){g.x, g.y} * carry + (f32x2){g.z, g.w}; }
	v_pk_mul_f32 v[0:1], v[0:1], v[20:21]
	v_pk_fma_f32 v[2:3], v[2:3], v[20:21], v[84:85]
	v_pk_mul_f32 v[0:1], v[0:1], v[22:23]
	v_pk_fma_f32 v[2:3], v[2:3], v[22:23], v[86:87]
	v_pk_mul_f32 v[0:1], v[0:1], v[24:25]
	v_pk_fma_f32 v[2:3], v[2:3], v[24:25], v[88:89]
	v_pk_mul_f32 v[0:1], v[0:1], v[26:27]
	v_pk_fma_f32 v[2:3], v[2:3], v[26:27], v[90:91]
	v_pk_mul_f32 v[0:1], v[0:1], v[28:29]
	v_pk_fma_f32 v[2:3], v[2:3], v[28:29], v[92:93]
	v_pk_mul_f32 v[0:1], v[0:1], v[30:31]
	v_pk_fma_f32 v[2:3], v[2:3], v[30:31], v[94:95]
	v_pk_mul_f32 v[0:1], v[0:1], v[32:33]
	v_pk_fma_f32 v[2:3], v[2:3], v[32:33], v[96:97]
	v_pk_mul_f32 v[0:1], v[0:1], v[34:35]
	v_pk_fma_f32 v[2:3], v[2:3], v[34:35], v[98:99]
	s_waitcnt vmcnt(32)
	v_pk_mul_f32 v[0:1], v[0:1], v[36:37]
	v_pk_fma_f32 v[2:3], v[2:3], v[36:37], v[100:101]
	v_pk_mul_f32 v[0:1], v[0:1], v[38:39]
	v_pk_fma_f32 v[2:3], v[2:3], v[38:39], v[102:103]
	v_pk_mul_f32 v[0:1], v[0:1], v[40:41]
	v_pk_fma_f32 v[2:3], v[2:3], v[40:41], v[104:105]
	v_pk_mul_f32 v[0:1], v[0:1], v[42:43]
	v_pk_fma_f32 v[2:3], v[2:3], v[42:43], v[106:107]
	v_pk_mul_f32 v[0:1], v[0:1], v[44:45]
	v_pk_fma_f32 v[2:3], v[2:3], v[44:45], v[108:109]
	v_pk_mul_f32 v[0:1], v[0:1], v[46:47]
	v_pk_fma_f32 v[2:3], v[2:3], v[46:47], v[110:111]
	v_pk_mul_f32 v[0:1], v[0:1], v[48:49]
	v_pk_fma_f32 v[2:3], v[2:3], v[48:49], v[112:113]
	v_pk_mul_f32 v[0:1], v[0:1], v[50:51]
	v_pk_fma_f32 v[2:3], v[2:3], v[50:51], v[114:115]
	s_waitcnt vmcnt(16)
	v_pk_mul_f32 v[0:1], v[0:1], v[52:53]
	v_pk_fma_f32 v[2:3], v[2:3], v[52:53], v[116:117]
	v_pk_mul_f32 v[0:1], v[0:1], v[54:55]
	v_pk_fma_f32 v[2:3], v[2:3], v[54:55], v[118:119]
	v_pk_mul_f32 v[0:1], v[0:1], v[56:57]
	v_pk_fma_f32 v[2:3], v[2:3], v[56:57], v[120:121]
	v_pk_mul_f32 v[0:1], v[0:1], v[58:59]
	v_pk_fma_f32 v[2:3], v[2:3], v[58:59], v[122:123]
	v_pk_mul_f32 v[0:1], v[0:1], v[60:61]
	v_pk_fma_f32 v[2:3], v[2:3], v[60:61], v[124:125]
	v_pk_mul_f32 v[0:1], v[0:1], v[62:63]
	v_pk_fma_f32 v[2:3], v[2:3], v[62:63], v[126:127]
	v_pk_mul_f32 v[0:1], v[0:1], v[64:65]
	v_pk_fma_f32 v[2:3], v[2:3], v[64:65], v[128:129]
	v_pk_mul_f32 v[0:1], v[0:1], v[66:67]
	v_pk_fma_f32 v[2:3], v[2:3], v[66:67], v[130:131]
	s_waitcnt vmcnt(0)
	v_pk_mul_f32 v[0:1], v[0:1], v[68:69]
	v_pk_fma_f32 v[2:3], v[2:3], v[68:69], v[132:133]
	v_pk_mul_f32 v[0:1], v[0:1], v[70:71]
	v_pk_fma_f32 v[2:3], v[2:3], v[70:71], v[134:135]
	v_pk_mul_f32 v[0:1], v[0:1], v[72:73]
	v_pk_fma_f32 v[2:3], v[2:3], v[72:73], v[136:137]
	v_pk_mul_f32 v[0:1], v[0:1], v[74:75]
	v_pk_fma_f32 v[2:3], v[2:3], v[74:75], v[138:139]
	v_pk_mul_f32 v[0:1], v[0:1], v[76:77]
	v_pk_fma_f32 v[2:3], v[2:3], v[76:77], v[140:141]
	v_pk_mul_f32 v[0:1], v[0:1], v[78:79]
	v_pk_fma_f32 v[2:3], v[2:3], v[78:79], v[142:143]
	v_pk_mul_f32 v[0:1], v[0:1], v[80:81]
	v_pk_fma_f32 v[2:3], v[2:3], v[80:81], v[144:145]
	v_pk_mul_f32 v[0:1], v[0:1], v[82:83]
	v_pk_fma_f32 v[2:3], v[2:3], v[82:83], v[146:147]
	v_lshl_add_u32 v10, v14, 4, 0
	ds_write_b128 v10, v[0:3]
	v_mov_b32_e32 v3, 0
	v_cmp_lt_i32_e64 s[0:1], 0, v15
	v_mov_b32_e32 v2, v3
	s_waitcnt lgkmcnt(0)
	s_barrier
	s_and_saveexec_b64 s[4:5], s[0:1]
	s_cbranch_execz .LBB0_167
	v_mov_b32_e32 v160, v161
	v_cmp_lt_u32_e64 s[0:1], 7, v15
	v_mov_b32_e32 v0, 0
	v_mov_b64_e32 v[2:3], v[160:161]
	s_and_saveexec_b64 s[6:7], s[0:1]
	s_cbranch_execz .LBB0_162
	v_mov_b32_e32 v2, 0
	v_lshl_add_u32 v1, v13, 4, 0
	v_and_b32_e32 v0, 0x7ffffff8, v15
	s_mov_b32 s10, 0
	s_mov_b64 s[8:9], 0
	v_mov_b32_e32 v3, v2

; __device__ __forceinline__ void phase_scan15(const Args& a, LAS unsigned char* lds, int wv_) { LAUNDER_IDS;
;     ...
;     for (int i = 0; i < 32; ++i) { const int c = dir ? 255 - (seg * 32 + i) : seg * 32 + i; *(f32x2*)(CR + (size_t)c * DM) = carry; const f32x2 av = *(const f32x2*)(GA + (size_t)c * DM), bv = *(const f32x2*)(GB + (size_t)c * DM); carry = av * carry + bv; }
.LBB0_168:
	v_mov_b32_e32 v149, 0
	v_lshl_add_u64 v[0:1], v[0:1], 0, v[148:149]
	global_store_dwordx2 v[0:1], v[2:3], off
	v_pk_fma_f32 v[2:3], v[2:3], v[20:21], v[84:85]
	v_lshl_add_u64 v[0:1], v[0:1], 0, s[100:101]
	global_store_dwordx2 v[0:1], v[2:3], off
	v_pk_fma_f32 v[2:3], v[2:3], v[22:23], v[86:87]
	v_lshl_add_u64 v[0:1], v[0:1], 0, s[100:101]
	global_store_dwordx2 v[0:1], v[2:3], off
	v_pk_fma_f32 v[2:3], v[2:3], v[24:25], v[88:89]
	v_lshl_add_u64 v[0:1], v[0:1], 0, s[100:101]
	global_store_dwordx2 v[0:1], v[2:3], off
	v_pk_fma_f32 v[2:3], v[2:3], v[26:27], v[90:91]
	v_lshl_add_u64 v[0:1], v[0:1], 0, s[100:101]
	global_store_dwordx2 v[0:1], v[2:3], off
	v_pk_fma_f32 v[2:3], v[2:3], v[28:29], v[92:93]
	v_lshl_add_u64 v[0:1], v[0:1], 0, s[100:101]
	global_store_dwordx2 v[0:1], v[2:3], off
	v_pk_fma_f32 v[2:3], v[2:3], v[30:31], v[94:95]
	v_lshl_add_u64 v[0:1], v[0:1], 0, s[100:101]
	global_store_dwordx2 v[0:1], v[2:3], off
	v_pk_fma_f32 v[2:3], v[2:3], v[32:33], v[96:97]
	v_lshl_add_u64 v[0:1], v[0:1], 0, s[100:101]
	global_store_dwordx2 v[0:1], v[2:3], off
	v_pk_fma_f32 v[2:3], v[2:3], v[34:35], v[98:99]
	v_lshl_add_u64 v[0:1], v[0:1], 0, s[100:101]
	global_store_dwordx2 v[0:1], v[2:3], off
	v_pk_fma_f32 v[2:3], v[2:3], v[36:37], v[100:101]
	v_lshl_add_u64 v[0:1], v[0:1], 0, s[100:101]
	global_store_dwordx2 v[0:1], v[2:3], off
	v_pk_fma_f32 v[2:3], v[2:3], v[38:39], v[102:103]
	v_lshl_add_u64 v[0:1], v[0:1], 0, s[100:101]
	global_store_dwordx2 v[0:1], v[2:3], off
	v_pk_fma_f32 v[2:3], v[2:3], v[40:41], v[104:105]
	v_lshl_add_u64 v[0:1], v[0:1], 0, s[100:101]
	global_store_dwordx2 v[0:1], v[2:3], off
	v_pk_fma_f32 v[2:3], v[2:3], v[42:43], v[106:107]
	v_lshl_add_u64 v[0:1], v[0:1], 0, s[100:101]
	global_store_dwordx2 v[0:1], v[2:3], off
	v_pk_fma_f32 v[2:3], v[2:3], v[44:45], v[108:109]
	v_lshl_add_u64 v[0:1], v[0:1], 0, s[100:101]
	global_store_dwordx2 v[0:1], v[2:3], off
	v_pk_fma_f32 v[2:3], v[2:3], v[46:47], v[110:111]
	v_lshl_add_u64 v[0:1], v[0:1], 0, s[100:101]
	global_store_dwordx2 v[0:1], v[2:3], off
	v_pk_fma_f32 v[2:3], v[2:3], v[48:49], v[112:113]
	v_lshl_add_u64 v[0:1], v[0:1], 0, s[100:101]
	global_store_dwordx2 v[0:1], v[2:3], off
	v_pk_fma_f32 v[2:3], v[2:3], v[50:51], v[114:115]
	v_lshl_add_u64 v[0:1], v[0:1], 0, s[100:101]
	global_store_dwordx2 v[0:1], v[2:3], off
	v_pk_fma_f32 v[2:3], v[2:3], v[52:53], v[116:117]
	v_lshl_add_u64 v[0:1], v[0:1], 0, s[100:101]
	global_store_dwordx2 v[0:1], v[2:3], off
	v_pk_fma_f32 v[2:3], v[2:3], v[54:55], v[118:119]
	v_lshl_add_u64 v[0:1], v[0:1], 0, s[100:101]
	global_store_dwordx2 v[0:1], v[2:3], off
	v_pk_fma_f32 v[2:3], v[2:3], v[56:57], v[120:121]
	v_lshl_add_u64 v[0:1], v[0:1], 0, s[100:101]
	global_store_dwordx2 v[0:1], v[2:3], off
	v_pk_fma_f32 v[2:3], v[2:3], v[58:59], v[122:123]
	v_lshl_add_u64 v[0:1], v[0:1], 0, s[100:101]
	global_store_dwordx2 v[0:1], v[2:3], off
	v_pk_fma_f32 v[2:3], v[2:3], v[60:61], v[124:125]
	v_lshl_add_u64 v[0:1], v[0:1], 0, s[100:101]
	global_store_dwordx2 v[0:1], v[2:3], off
	v_pk_fma_f32 v[2:3], v[2:3], v[62:63], v[126:127]
	v_lshl_add_u64 v[0:1], v[0:1], 0, s[100:101]
	global_store_dwordx2 v[0:1], v[2:3], off
	v_pk_fma_f32 v[2:3], v[2:3], v[64:65], v[128:129]
	v_lshl_add_u64 v[0:1], v[0:1], 0, s[100:101]
	global_store_dwordx2 v[0:1], v[2:3], off
	v_pk_fma_f32 v[2:3], v[2:3], v[66:67], v[130:131]
	v_lshl_add_u64 v[0:1], v[0:1], 0, s[100:101]
	global_store_dwordx2 v[0:1], v[2:3], off
	v_pk_fma_f32 v[2:3], v[2:3], v[68:69], v[132:133]
	v_lshl_add_u64 v[0:1], v[0:1], 0, s[100:101]
	global_store_dwordx2 v[0:1], v[2:3], off
	v_pk_fma_f32 v[2:3], v[2:3], v[70:71], v[134:135]
	v_lshl_add_u64 v[0:1], v[0:1], 0, s[100:101]
	global_store_dwordx2 v[0:1], v[2:3], off
	v_pk_fma_f32 v[2:3], v[2:3], v[72:73], v[136:137]
	v_lshl_add_u64 v[0:1], v[0:1], 0, s[100:101]
	global_store_dwordx2 v[0:1], v[2:3], off
	v_pk_fma_f32 v[2:3], v[2:3], v[74:75], v[138:139]
	v_lshl_add_u64 v[0:1], v[0:1], 0, s[100:101]
	global_store_dwordx2 v[0:1], v[2:3], off
	v_pk_fma_f32 v[2:3], v[2:3], v[76:77], v[140:141]
	v_lshl_add_u64 v[0:1], v[0:1], 0, s[100:101]
	global_store_dwordx2 v[0:1], v[2:3], off
	v_pk_fma_f32 v[2:3], v[2:3], v[78:79], v[142:143]
	v_lshl_add_u64 v[0:1], v[0:1], 0, s[100:101]
	global_store_dwordx2 v[0:1], v[2:3], off
	v_pk_fma_f32 v[2:3], v[2:3], v[80:81], v[144:145]
	v_lshl_add_u64 v[0:1], v[0:1], 0, s[100:101]
	global_store_dwordx2 v[0:1], v[2:3], off

; __device__ __forceinline__ unsigned cvt_pk_bf16(float lo, float hi) { unsigned r; asm volatile("v_cvt_pk_bf16_f32 %0, %1, %2" : "=v"(r) : "v"(lo), "v"(hi)); return r; }
; __device__ __forceinline__ int crow(int r, int hi) { return (r & 3) + 8 * (r >> 2) + 4 * hi; }
; #define WAIT_BAR() asm volatile("s_waitcnt vmcnt(0) lgkmcnt(0)\n\ts_barrier" ::: "memory")
; __device__ __forceinline__ void attn_unit(const bf16_t* __restrict__ Qb, const bf16_t* __restrict__ Kn, const bf16_t* __restrict__ Vh, const bf16_t* __restrict__ Kr,
;                                           bf16_t* __restrict__ Ob, int seq, char* lds, int wv_) { LAUNDER_IDS;
;     ...
;     if (hi == 0) li_l[r32] = l_reg; asm volatile("s_waitcnt lgkmcnt(0)" ::: "memory");
;     float rli[16];
; #pragma unroll
;     for (int r = 0; r < 16; ++r) rli[r] = __builtin_amdgcn_rcpf(li_l[crow(r, hi)]);
;     bf16_t* Ow = Ob + (long)(wid * QBLK) * LDO;
; #pragma unroll
;     for (int r = 0; r < 16; ++r) { const int orow = crow(r, hi);
; #pragma unroll
;         for (int d0 = 0; d0 < 4; ++d0) Ow[(long)orow * LDO + d0 * 32 + r32] = (bf16_t)(cvt_pk_bf16(o[d0][r] * rli[r], 0.f) & 0xffffu); }
;     WAIT_BAR();
.LBB0_213:
	s_or_b64 exec, exec, s[0:1]
	s_waitcnt lgkmcnt(0)
	v_add_u32_e32 v72, s5, v160
	ds_read_b128 v[64:67], v72
	ds_read_b128 v[68:71], v72 offset:32
	ds_read_b128 v[84:87], v72 offset:64
	ds_read_b128 v[88:91], v72 offset:96
	s_lshl_b32 s0, s4, 12
	v_readlane_b32 s1, v251, 52
	s_add_u32 s4, s1, s0
	v_readlane_b32 s0, v251, 53
	s_addc_u32 s6, s0, 0
	s_lshl_b32 s0, s3, 7
	s_ashr_i32 s1, s0, 31
	s_lshl_b64 s[0:1], s[0:1], 1
	s_add_u32 s3, s4, s0
	s_addc_u32 s4, s6, s1
	s_ashr_i32 s13, s12, 31
	s_lshl_b64 s[0:1], s[12:13], 12
	s_add_u32 s0, s3, s0
	s_addc_u32 s1, s4, s1
	s_lshl_b32 s13, s12, 6
	s_add_i32 s13, s13, 0x1a000
	v_lshl_add_u32 v92, v185, 5, v183
	v_lshlrev_b32_e32 v93, 8, v185
	v_lshl_add_u32 v93, v183, 1, v93
	v_add_u32_e32 v93, s13, v93
	v_lshl_add_u32 v94, v92, 4, s13
	v_lshrrev_b32_e32 v95, 2, v92
	v_lshlrev_b32_e32 v95, 12, v95
	v_and_b32_e32 v96, 3, v92
	v_lshl_add_u32 v160, v96, 4, v95
	v_lshl_add_u64 v[96:97], s[0:1], 0, v[160:161]
	s_add_u32 s0, s0, 0x10000
	s_addc_u32 s1, s1, 0
	v_lshl_add_u64 v[98:99], s[0:1], 0, v[160:161]
	s_waitcnt lgkmcnt(0)
	v_rcp_f32_e32 v64, v64
	v_rcp_f32_e32 v65, v65
	v_rcp_f32_e32 v66, v66
	v_rcp_f32_e32 v67, v67
	v_rcp_f32_e32 v68, v68
	v_rcp_f32_e32 v69, v69
	v_rcp_f32_e32 v70, v70
	v_rcp_f32_e32 v71, v71
	v_rcp_f32_e32 v84, v84
	v_rcp_f32_e32 v85, v85
	v_rcp_f32_e32 v86, v86
	v_rcp_f32_e32 v87, v87
	v_rcp_f32_e32 v88, v88
	v_rcp_f32_e32 v89, v89
	v_rcp_f32_e32 v90, v90
	v_rcp_f32_e32 v91, v91
	v_mul_f32_e32 v100, v0, v64
	v_mul_f32_e32 v101, v1, v65
	v_mul_f32_e32 v102, v2, v66
	v_mul_f32_e32 v103, v3, v67
	v_mul_f32_e32 v104, v4, v68
	v_mul_f32_e32 v105, v5, v69
	v_mul_f32_e32 v106, v6, v70
	v_mul_f32_e32 v107, v7, v71
	v_mul_f32_e32 v108, v8, v84
	v_mul_f32_e32 v109, v9, v85
	v_mul_f32_e32 v110, v10, v86
	v_mul_f32_e32 v111, v11, v87
	v_mul_f32_e32 v112, v12, v88
	v_mul_f32_e32 v113, v13, v89
	v_mul_f32_e32 v114, v14, v90
	v_mul_f32_e32 v115, v15, v91
	v_cvt_pk_bf16_f32 v100, v100, v161
	v_cvt_pk_bf16_f32 v101, v101, v161
	v_cvt_pk_bf16_f32 v102, v102, v161
	v_cvt_pk_bf16_f32 v103, v103, v161
	v_cvt_pk_bf16_f32 v104, v104, v161
	v_cvt_pk_bf16_f32 v105, v105, v161
	v_cvt_pk_bf16_f32 v106, v106, v161
	v_cvt_pk_bf16_f32 v107, v107, v161
	v_cvt_pk_bf16_f32 v108, v108, v161
	v_cvt_pk_bf16_f32 v109, v109, v161
	v_cvt_pk_bf16_f32 v110, v110, v161
	v_cvt_pk_bf16_f32 v111, v111, v161
	v_cvt_pk_bf16_f32 v112, v112, v161
	v_cvt_pk_bf16_f32 v113, v113, v161
	v_cvt_pk_bf16_f32 v114, v114, v161
	v_cvt_pk_bf16_f32 v115, v115, v161
	ds_write_b16 v93, v100
	ds_write_b16 v93, v101 offset:64
	ds_write_b16 v93, v102 offset:128
	ds_write_b16 v93, v103 offset:192
	ds_write_b16 v93, v104 offset:512
	ds_write_b16 v93, v105 offset:576
	ds_write_b16 v93, v106 offset:640
	ds_write_b16 v93, v107 offset:704
	ds_write_b16 v93, v108 offset:1024
	ds_write_b16 v93, v109 offset:1088
	ds_write_b16 v93, v110 offset:1152
	ds_write_b16 v93, v111 offset:1216
	ds_write_b16 v93, v112 offset:1536
	ds_write_b16 v93, v113 offset:1600
	ds_write_b16 v93, v114 offset:1664
	ds_write_b16 v93, v115 offset:1728
	s_waitcnt lgkmcnt(0)
	ds_read_b128 v[120:123], v94
	ds_read_b128 v[124:127], v94 offset:1024
	s_waitcnt lgkmcnt(0)
	global_store_dwordx4 v[96:97], v[120:123], off
	global_store_dwordx4 v[98:99], v[124:127], off
	v_mul_f32_e32 v100, v48, v64
	v_mul_f32_e32 v101, v49, v65
	v_mul_f32_e32 v102, v50, v66
	v_mul_f32_e32 v103, v51, v67
	v_mul_f32_e32 v104, v52, v68
	v_mul_f32_e32 v105, v53, v69
	v_mul_f32_e32 v106, v54, v70
	v_mul_f32_e32 v107, v55, v71
	v_mul_f32_e32 v108, v56, v84
	v_mul_f32_e32 v109, v57, v85
	v_mul_f32_e32 v110, v58, v86
	v_mul_f32_e32 v111, v59, v87
	v_mul_f32_e32 v112, v60, v88
	v_mul_f32_e32 v113, v61, v89
	v_mul_f32_e32 v114, v62, v90
	v_mul_f32_e32 v115, v63, v91
	v_cvt_pk_bf16_f32 v100, v100, v161
	v_cvt_pk_bf16_f32 v101, v101, v161
	v_cvt_pk_bf16_f32 v102, v102, v161
	v_cvt_pk_bf16_f32 v103, v103, v161
	v_cvt_pk_bf16_f32 v104, v104, v161
	v_cvt_pk_bf16_f32 v105, v105, v161
	v_cvt_pk_bf16_f32 v106, v106, v161
	v_cvt_pk_bf16_f32 v107, v107, v161
	v_cvt_pk_bf16_f32 v108, v108, v161
	v_cvt_pk_bf16_f32 v109, v109, v161
	v_cvt_pk_bf16_f32 v110, v110, v161
	v_cvt_pk_bf16_f32 v111, v111, v161
	v_cvt_pk_bf16_f32 v112, v112, v161
	v_cvt_pk_bf16_f32 v113, v113, v161
	v_cvt_pk_bf16_f32 v114, v114, v161
	v_cvt_pk_bf16_f32 v115, v115, v161
	ds_write_b16 v93, v100
	ds_write_b16 v93, v101 offset:64
	ds_write_b16 v93, v102 offset:128
	ds_write_b16 v93, v103 offset:192
	ds_write_b16 v93, v104 offset:512
	ds_write_b16 v93, v105 offset:576
	ds_write_b16 v93, v106 offset:640
	ds_write_b16 v93, v107 offset:704
	ds_write_b16 v93, v108 offset:1024
	ds_write_b16 v93, v109 offset:1088
	ds_write_b16 v93, v110 offset:1152
	ds_write_b16 v93, v111 offset:1216
	ds_write_b16 v93, v112 offset:1536
	ds_write_b16 v93, v113 offset:1600
	ds_write_b16 v93, v114 offset:1664
	ds_write_b16 v93, v115 offset:1728
	s_waitcnt lgkmcnt(0)
; __device__ __forceinline__ unsigned cvt_pk_bf16(float lo, float hi) { unsigned r; asm volatile("v_cvt_pk_bf16_f32 %0, %1, %2" : "=v"(r) : "v"(lo), "v"(hi)); return r; }
; __device__ __forceinline__ int crow(int r, int hi) { return (r & 3) + 8 * (r >> 2) + 4 * hi; }
; #define WAIT_BAR() asm volatile("s_waitcnt vmcnt(0) lgkmcnt(0)\n\ts_barrier" ::: "memory")
; __device__ __forceinline__ void attn_unit(const bf16_t* __restrict__ Qb, const bf16_t* __restrict__ Kn, const bf16_t* __restrict__ Vh, const bf16_t* __restrict__ Kr,
;                                           bf16_t* __restrict__ Ob, int seq, char* lds, int wv_) { LAUNDER_IDS;
;     ...
;     bf16_t* Ow = Ob + (long)(wid * QBLK) * LDO;
; #pragma unroll
;     for (int r = 0; r < 16; ++r) { const int orow = crow(r, hi);
; #pragma unroll
;         for (int d0 = 0; d0 < 4; ++d0) Ow[(long)orow * LDO + d0 * 32 + r32] = (bf16_t)(cvt_pk_bf16(o[d0][r] * rli[r], 0.f) & 0xffffu); }
;     WAIT_BAR();
; __device__ __forceinline__ void phase_attention(const Args& a, char* lds, int wv_) { LAUNDER_IDS;
;     ...
;     for (int u = vcu; u < 512; u += G) { const int h = u >> 5, qb = u & 31;
;         att::attn_unit(Q + (size_t)qb * 256 * NQ + h * 192, KV + h * 256, KV + h * 256 + 128, KPE, O + (size_t)qb * 256 * DM + h * 128, SEQ, lds, wv_); }
	ds_read_b128 v[120:123], v94
	ds_read_b128 v[124:127], v94 offset:1024
	s_waitcnt lgkmcnt(0)
	global_store_dwordx4 v[96:97], v[120:123], off offset:64
	global_store_dwordx4 v[98:99], v[124:127], off offset:64
	v_mul_f32_e32 v100, v32, v64
	v_mul_f32_e32 v101, v33, v65
	v_mul_f32_e32 v102, v34, v66
	v_mul_f32_e32 v103, v35, v67
	v_mul_f32_e32 v104, v36, v68
	v_mul_f32_e32 v105, v37, v69
	v_mul_f32_e32 v106, v38, v70
	v_mul_f32_e32 v107, v39, v71
	v_mul_f32_e32 v108, v40, v84
	v_mul_f32_e32 v109, v41, v85
	v_mul_f32_e32 v110, v42, v86
	v_mul_f32_e32 v111, v43, v87
	v_mul_f32_e32 v112, v44, v88
	v_mul_f32_e32 v113, v45, v89
	v_mul_f32_e32 v114, v46, v90
	v_mul_f32_e32 v115, v47, v91
	v_cvt_pk_bf16_f32 v100, v100, v161
	v_cvt_pk_bf16_f32 v101, v101, v161
	v_cvt_pk_bf16_f32 v102, v102, v161
	v_cvt_pk_bf16_f32 v103, v103, v161
	v_cvt_pk_bf16_f32 v104, v104, v161
	v_cvt_pk_bf16_f32 v105, v105, v161
	v_cvt_pk_bf16_f32 v106, v106, v161
	v_cvt_pk_bf16_f32 v107, v107, v161
	v_cvt_pk_bf16_f32 v108, v108, v161
	v_cvt_pk_bf16_f32 v109, v109, v161
	v_cvt_pk_bf16_f32 v110, v110, v161
	v_cvt_pk_bf16_f32 v111, v111, v161
	v_cvt_pk_bf16_f32 v112, v112, v161
	v_cvt_pk_bf16_f32 v113, v113, v161
	v_cvt_pk_bf16_f32 v114, v114, v161
	v_cvt_pk_bf16_f32 v115, v115, v161
	ds_write_b16 v93, v100
	ds_write_b16 v93, v101 offset:64
	ds_write_b16 v93, v102 offset:128
	ds_write_b16 v93, v103 offset:192
	ds_write_b16 v93, v104 offset:512
	ds_write_b16 v93, v105 offset:576
	ds_write_b16 v93, v106 offset:640
	ds_write_b16 v93, v107 offset:704
	ds_write_b16 v93, v108 offset:1024
	ds_write_b16 v93, v109 offset:1088
	ds_write_b16 v93, v110 offset:1152
	ds_write_b16 v93, v111 offset:1216
	ds_write_b16 v93, v112 offset:1536
	ds_write_b16 v93, v113 offset:1600
	ds_write_b16 v93, v114 offset:1664
	ds_write_b16 v93, v115 offset:1728
	s_waitcnt lgkmcnt(0)
	ds_read_b128 v[120:123], v94
	ds_read_b128 v[124:127], v94 offset:1024
	s_waitcnt lgkmcnt(0)
	global_store_dwordx4 v[96:97], v[120:123], off offset:128
	global_store_dwordx4 v[98:99], v[124:127], off offset:128
	v_mul_f32_e32 v100, v16, v64
	v_mul_f32_e32 v101, v17, v65
	v_mul_f32_e32 v102, v18, v66
	v_mul_f32_e32 v103, v19, v67
	v_mul_f32_e32 v104, v20, v68
	v_mul_f32_e32 v105, v21, v69
	v_mul_f32_e32 v106, v22, v70
	v_mul_f32_e32 v107, v23, v71
	v_mul_f32_e32 v108, v24, v84
	v_mul_f32_e32 v109, v25, v85
	v_mul_f32_e32 v110, v26, v86
	v_mul_f32_e32 v111, v27, v87
	v_mul_f32_e32 v112, v28, v88
	v_mul_f32_e32 v113, v29, v89
	v_mul_f32_e32 v114, v30, v90
	v_mul_f32_e32 v115, v31, v91
	v_cvt_pk_bf16_f32 v100, v100, v161
	v_cvt_pk_bf16_f32 v101, v101, v161
	v_cvt_pk_bf16_f32 v102, v102, v161
	v_cvt_pk_bf16_f32 v103, v103, v161
	v_cvt_pk_bf16_f32 v104, v104, v161
	v_cvt_pk_bf16_f32 v105, v105, v161
	v_cvt_pk_bf16_f32 v106, v106, v161
	v_cvt_pk_bf16_f32 v107, v107, v161
	v_cvt_pk_bf16_f32 v108, v108, v161
	v_cvt_pk_bf16_f32 v109, v109, v161
	v_cvt_pk_bf16_f32 v110, v110, v161
	v_cvt_pk_bf16_f32 v111, v111, v161
	v_cvt_pk_bf16_f32 v112, v112, v161
	v_cvt_pk_bf16_f32 v113, v113, v161
	v_cvt_pk_bf16_f32 v114, v114, v161
	v_cvt_pk_bf16_f32 v115, v115, v161
	ds_write_b16 v93, v100
	ds_write_b16 v93, v101 offset:64
	ds_write_b16 v93, v102 offset:128
	ds_write_b16 v93, v103 offset:192
	ds_write_b16 v93, v104 offset:512
	ds_write_b16 v93, v105 offset:576
	ds_write_b16 v93, v106 offset:640
	ds_write_b16 v93, v107 offset:704
	ds_write_b16 v93, v108 offset:1024
	ds_write_b16 v93, v109 offset:1088
	ds_write_b16 v93, v110 offset:1152
	ds_write_b16 v93, v111 offset:1216
	ds_write_b16 v93, v112 offset:1536
	ds_write_b16 v93, v113 offset:1600
	ds_write_b16 v93, v114 offset:1664
	ds_write_b16 v93, v115 offset:1728
	s_waitcnt lgkmcnt(0)
	ds_read_b128 v[120:123], v94
	ds_read_b128 v[124:127], v94 offset:1024
	s_waitcnt lgkmcnt(0)
	global_store_dwordx4 v[96:97], v[120:123], off offset:192
	global_store_dwordx4 v[98:99], v[124:127], off offset:192
	s_waitcnt vmcnt(0) lgkmcnt(0)
	s_barrier
	s_add_i32 s2, s2, s76
	s_cmpk_lt_i32 s2, 0x200
	s_cbranch_scc0 .LBB0_200
